# second peeled K-loop copy for tiles following an epilogue: DMA waits leave the epilogue's trailing stores in flight
# speedup vs baseline: 1.0131x; 1.0028x over previous
.LBB0_361:
	s_add_u32 s34, s14, 0
	s_addc_u32 s21, s15, s21
	s_add_u32 s34, s34, s19
	s_addc_u32 s35, s21, 0
	s_add_u32 s19, s14, 0
	s_addc_u32 s21, s15, s25
	s_add_u32 s36, s19, s20
	s_addc_u32 s37, s21, 0
	s_add_i32 m0, s73, 0x18000
	v_lshl_add_u64 v[4:5], v[4:5], 0, s[86:87]
	s_waitcnt vmcnt(4)
	s_barrier
	global_load_lds_dwordx4 v[4:5], off
	v_lshl_add_u64 v[4:5], v[6:7], 0, s[86:87]
	s_add_i32 m0, s73, 0x1a000
	s_add_i32 s77, s73, 0x8000
	global_load_lds_dwordx4 v[4:5], off
	v_lshl_add_u64 v[4:5], v[8:9], 0, s[86:87]
	s_mov_b32 m0, s77
	s_add_i32 s64, s73, 0xa000
	global_load_lds_dwordx4 v[4:5], off
	v_lshl_add_u64 v[4:5], v[10:11], 0, s[86:87]
	s_mov_b32 m0, s64
	s_lshr_b32 s19, s51, 26
	global_load_lds_dwordx4 v[4:5], off
	s_add_i32 m0, s73, 0x1c000
	v_lshl_add_u64 v[4:5], v[12:13], 0, s[86:87]
	global_load_lds_dwordx4 v[4:5], off
	v_lshl_add_u64 v[4:5], v[14:15], 0, s[86:87]
	s_add_i32 m0, s73, 0x1e000
	s_add_i32 s19, s50, s19
	global_load_lds_dwordx4 v[4:5], off
	v_lshlrev_b32_e32 v16, 2, v228
	s_ashr_i32 s67, s19, 6
	v_lshl_or_b32 v1, v228, 6, v230
	s_lshl_b32 s19, s38, 13
	v_and_b32_e32 v16, 32, v16
	v_bitop3_b32 v1, v1, s19, v16 bitop3:0xde
	s_lshl_b32 s19, s39, 5
	s_and_b32 s46, s19, 0x60
	s_cmp_gt_i32 s50, 63
	v_lshl_or_b32 v199, s38, 6, v228
	s_cselect_b64 s[38:39], -1, 0
	s_ashr_i32 s20, s18, 31
	s_lshr_b32 s20, s20, 29
	s_add_i32 s20, s18, s20
	s_ashr_i32 s44, s20, 3
	s_and_b32 s20, s20, -8
	s_ashr_i32 s19, s16, 31
	s_ashr_i32 s53, s95, 31
	s_ashr_i32 s25, s24, 31
	s_sub_i32 s45, s18, s20
	s_add_i32 s65, s44, 1
	s_lshl_b32 s74, s9, 3
	s_add_i32 s75, s67, -2
	s_ashr_i32 s9, s17, 31
	s_add_u32 s80, s17, s16
	v_sub_co_u32_e64 v4, s[16:17], s1, 1
	s_addc_u32 s82, s9, s19
	s_xor_b64 s[40:41], s[16:17], -1
	s_cmp_gt_i32 s1, 3
	s_cselect_b64 s[42:43], -1, 0
	s_cmp_lg_u32 s1, 4
	s_cselect_b64 s[48:49], -1, 0
	s_ashr_i32 s9, s8, 31
	s_lshl_b64 s[8:9], s[8:9], 2
	s_add_u32 s84, s14, s8
	s_addc_u32 s16, s15, s9
	s_add_u32 s17, s14, 0x198100
	s_addc_u32 s18, s15, 0
	s_abs_i32 s20, s74
	v_lshlrev_b32_e32 v204, 10, v4
	v_cmp_ne_u32_e64 s[8:9], 0, v4
	v_cvt_f32_u32_e32 v4, s20
	s_sub_i32 s1, 0, s20
	s_waitcnt vmcnt(6)
	s_mov_b32 s66, 0
	v_rcp_iflag_f32_e32 v4, v4
	v_lshl_or_b32 v238, s46, 7, v231
	v_or_b32_e32 v239, s46, v229
	v_ashrrev_i32_e32 v205, 31, v204
	v_mul_f32_e32 v4, 0x4f7ffffe, v4
	v_cvt_u32_f32_e32 v4, v4
	s_ashr_i32 s19, s74, 31
	v_add_u32_e32 v240, 0, v1
	s_lshl_b32 s46, s46, 2
	v_readfirstlane_b32 s14, v4
	s_mul_i32 s1, s1, s14
	s_mul_hi_u32 s1, s14, s1
	v_lshlrev_b32_e32 v4, 1, v226
	s_add_i32 s21, s14, s1
	v_mad_u64_u32 v[4:5], s[14:15], v4, s50, v[196:197]
	v_mov_b32_e32 v5, v2
	v_lshl_add_u64 v[206:207], s[28:29], 0, v[4:5]
	v_lshlrev_b32_e32 v4, 1, v227
	v_mad_u64_u32 v[4:5], s[14:15], v4, s50, v[196:197]
	v_mov_b32_e32 v5, v2
	v_lshl_add_u64 v[208:209], s[28:29], 0, v[4:5]
	s_barrier
	s_mov_b32 s32, 0
	s_branch .LBB0_363
.LBB0_362:
	s_and_b64 vcc, exec, s[14:15]
	s_mov_b32 s0, s52
	s_mov_b32 s71, s70
	s_mov_b64 s[10:11], s[96:97]
	s_mov_b64 s[4:5], s[50:51]
	s_cbranch_vccnz .LBB0_455
	s_mov_b32 s32, 1

.Lk_go:
	s_add_u32 s4, s4, 0x80
	s_addc_u32 s5, s5, 0
	s_add_u32 s1, s10, 0x100
	s_addc_u32 vcc_lo, s11, 0
	s_mov_b32 s10, 0
	s_cmp_eq_u32 s32, 1
	s_cbranch_scc1 .Lk_goB
	s_add_i32 vcc_hi, s10, 2
	s_add_u32 s56, s4, 0x80
	s_addc_u32 s11, s5, 0
	s_add_i32 s98, 0, 0x10000
	v_add_u32_e32 v1, s98, v238
	ds_read_b128 v[132:135], v1
	ds_read_b128 v[136:139], v1 offset:1024
	ds_read_b128 v[140:143], v1 offset:2048
	ds_read_b128 v[144:147], v1 offset:3072
	s_cmp_eq_u32 s75, s10
	s_cselect_b32 s10, s50, s56
	s_cselect_b32 s11, s51, s11
	s_cselect_b32 s57, s97, vcc_lo
	s_cselect_b32 s56, s96, s1
	v_lshl_add_u64 v[180:181], s[4:5], 0, v[206:207]
	s_add_i32 m0, s73, 0xc000
	ds_read_b128 v[148:151], v240
	ds_read_b128 v[152:155], v240 offset:1024
	ds_read_b128 v[156:159], v240 offset:2048
	ds_read_b128 v[160:163], v240 offset:3072
	ds_read_b128 v[164:167], v240 offset:4096
	ds_read_b128 v[168:171], v240 offset:5120
	ds_read_b128 v[172:175], v240 offset:6144
	ds_read_b128 v[176:179], v240 offset:7168
	global_load_lds_dwordx4 v[180:181], off
	v_lshl_add_u64 v[180:181], s[4:5], 0, v[208:209]
	s_add_i32 m0, s73, 0xe000
	s_nop 0
	global_load_lds_dwordx4 v[180:181], off
	s_waitcnt lgkmcnt(8)
	s_waitcnt vmcnt(10)
	s_barrier
	s_waitcnt lgkmcnt(0)
	s_setprio 1
	s_waitcnt lgkmcnt(0)
	v_mfma_f32_16x16x32_f16 v[124:127], v[132:135], v[148:151], 0
	v_mfma_f32_16x16x32_f16 v[128:131], v[140:143], v[148:151], 0
	v_mfma_f32_16x16x32_f16 v[108:111], v[132:135], v[156:159], 0
	v_mfma_f32_16x16x32_f16 v[112:115], v[140:143], v[156:159], 0
	v_mfma_f32_16x16x32_f16 v[92:95], v[132:135], v[164:167], 0
	v_mfma_f32_16x16x32_f16 v[96:99], v[140:143], v[164:167], 0
	v_mfma_f32_16x16x32_f16 v[76:79], v[132:135], v[172:175], 0
	v_mfma_f32_16x16x32_f16 v[80:83], v[140:143], v[172:175], 0
	v_mfma_f32_16x16x32_f16 v[124:127], v[136:139], v[152:155], v[124:127]
	v_mfma_f32_16x16x32_f16 v[128:131], v[144:147], v[152:155], v[128:131]
	v_mfma_f32_16x16x32_f16 v[108:111], v[136:139], v[160:163], v[108:111]
	v_mfma_f32_16x16x32_f16 v[112:115], v[144:147], v[160:163], v[112:115]
	v_mfma_f32_16x16x32_f16 v[92:95], v[136:139], v[168:171], v[92:95]
	v_mfma_f32_16x16x32_f16 v[96:99], v[144:147], v[168:171], v[96:99]
	v_mfma_f32_16x16x32_f16 v[76:79], v[136:139], v[176:179], v[76:79]
	v_mfma_f32_16x16x32_f16 v[80:83], v[144:147], v[176:179], v[80:83]
	s_setprio 0
	s_barrier
	s_add_i32 s98, s98, s72
	v_add_u32_e32 v1, s58, v238
	v_lshl_add_u64 v[210:211], s[56:57], 0, v[200:201]
	s_mov_b32 m0, s98
	ds_read_b128 v[180:183], v1
	ds_read_b128 v[184:187], v1 offset:1024
	ds_read_b128 v[188:191], v1 offset:2048
	ds_read_b128 v[192:195], v1 offset:3072
	global_load_lds_dwordx4 v[210:211], off
	v_lshl_add_u64 v[212:213], s[56:57], 0, v[202:203]
	s_add_i32 m0, s98, 0x2000
	s_nop 0
	global_load_lds_dwordx4 v[212:213], off
	s_waitcnt vmcnt(10)
	s_barrier
	s_waitcnt lgkmcnt(0)
	s_setprio 1
	s_waitcnt lgkmcnt(0)
	v_mfma_f32_16x16x32_f16 v[116:119], v[180:183], v[148:151], 0
	v_mfma_f32_16x16x32_f16 v[120:123], v[188:191], v[148:151], 0
	v_mfma_f32_16x16x32_f16 v[100:103], v[180:183], v[156:159], 0
	v_mfma_f32_16x16x32_f16 v[104:107], v[188:191], v[156:159], 0
	v_mfma_f32_16x16x32_f16 v[84:87], v[180:183], v[164:167], 0
	v_mfma_f32_16x16x32_f16 v[88:91], v[188:191], v[164:167], 0
	v_mfma_f32_16x16x32_f16 v[68:71], v[180:183], v[172:175], 0
	v_mfma_f32_16x16x32_f16 v[72:75], v[188:191], v[172:175], 0
	v_mfma_f32_16x16x32_f16 v[116:119], v[184:187], v[152:155], v[116:119]
	v_mfma_f32_16x16x32_f16 v[120:123], v[192:195], v[152:155], v[120:123]
	v_mfma_f32_16x16x32_f16 v[100:103], v[184:187], v[160:163], v[100:103]
	v_mfma_f32_16x16x32_f16 v[104:107], v[192:195], v[160:163], v[104:107]
	v_mfma_f32_16x16x32_f16 v[84:87], v[184:187], v[168:171], v[84:87]
	v_mfma_f32_16x16x32_f16 v[88:91], v[192:195], v[168:171], v[88:91]
	v_mfma_f32_16x16x32_f16 v[68:71], v[184:187], v[176:179], v[68:71]
	v_mfma_f32_16x16x32_f16 v[72:75], v[192:195], v[176:179], v[72:75]
	s_setprio 0
	s_mov_b32 m0, s73
	v_lshl_add_u64 v[214:215], s[10:11], 0, v[200:201]
	s_barrier
	ds_read_b128 v[148:151], v240 offset:16384
	ds_read_b128 v[152:155], v240 offset:17408
	ds_read_b128 v[156:159], v240 offset:18432
	ds_read_b128 v[160:163], v240 offset:19456
	ds_read_b128 v[164:167], v240 offset:20480
	ds_read_b128 v[168:171], v240 offset:21504
	ds_read_b128 v[172:175], v240 offset:22528
	ds_read_b128 v[176:179], v240 offset:23552
	global_load_lds_dwordx4 v[214:215], off
	v_lshl_add_u64 v[216:217], s[10:11], 0, v[202:203]
	s_mov_b32 m0, s78
	s_nop 0
	global_load_lds_dwordx4 v[216:217], off
	s_barrier
	s_waitcnt lgkmcnt(0)
	s_setprio 1
	s_waitcnt lgkmcnt(0)
	v_mfma_f32_16x16x32_f16 v[60:63], v[132:135], v[148:151], 0
	v_mfma_f32_16x16x32_f16 v[64:67], v[140:143], v[148:151], 0
	v_mfma_f32_16x16x32_f16 v[44:47], v[132:135], v[156:159], 0
	v_mfma_f32_16x16x32_f16 v[48:51], v[140:143], v[156:159], 0
	v_mfma_f32_16x16x32_f16 v[28:31], v[132:135], v[164:167], 0
	v_mfma_f32_16x16x32_f16 v[32:35], v[140:143], v[164:167], 0
	v_mfma_f32_16x16x32_f16 v[12:15], v[132:135], v[172:175], 0
	v_mfma_f32_16x16x32_f16 v[16:19], v[140:143], v[172:175], 0
	v_mfma_f32_16x16x32_f16 v[60:63], v[136:139], v[152:155], v[60:63]
	v_mfma_f32_16x16x32_f16 v[64:67], v[144:147], v[152:155], v[64:67]
	v_mfma_f32_16x16x32_f16 v[44:47], v[136:139], v[160:163], v[44:47]
	v_mfma_f32_16x16x32_f16 v[48:51], v[144:147], v[160:163], v[48:51]
	v_mfma_f32_16x16x32_f16 v[28:31], v[136:139], v[168:171], v[28:31]
	v_mfma_f32_16x16x32_f16 v[32:35], v[144:147], v[168:171], v[32:35]
	v_mfma_f32_16x16x32_f16 v[12:15], v[136:139], v[176:179], v[12:15]
	v_mfma_f32_16x16x32_f16 v[16:19], v[144:147], v[176:179], v[16:19]
	s_setprio 0
	s_barrier
	s_add_u32 s56, s56, s28
	s_addc_u32 s57, s57, s29
	s_add_i32 s98, s58, s72
	v_lshl_add_u64 v[218:219], s[56:57], 0, v[200:201]
	s_mov_b32 m0, s98
	v_lshl_add_u64 v[220:221], s[56:57], 0, v[202:203]
	global_load_lds_dwordx4 v[218:219], off
	s_add_i32 m0, s98, 0x2000
	s_nop 0
	global_load_lds_dwordx4 v[220:221], off
	s_waitcnt vmcnt(10)
	s_barrier
	s_setprio 1
	v_mfma_f32_16x16x32_f16 v[52:55], v[180:183], v[148:151], 0
	v_mfma_f32_16x16x32_f16 v[56:59], v[188:191], v[148:151], 0
	v_mfma_f32_16x16x32_f16 v[36:39], v[180:183], v[156:159], 0
	v_mfma_f32_16x16x32_f16 v[40:43], v[188:191], v[156:159], 0
	v_mfma_f32_16x16x32_f16 v[20:23], v[180:183], v[164:167], 0
	v_mfma_f32_16x16x32_f16 v[24:27], v[188:191], v[164:167], 0
	v_mfma_f32_16x16x32_f16 v[8:11], v[180:183], v[172:175], 0
	v_mfma_f32_16x16x32_f16 v[4:7], v[188:191], v[172:175], 0
	v_mfma_f32_16x16x32_f16 v[52:55], v[184:187], v[152:155], v[52:55]
	v_mfma_f32_16x16x32_f16 v[56:59], v[192:195], v[152:155], v[56:59]
	v_mfma_f32_16x16x32_f16 v[36:39], v[184:187], v[160:163], v[36:39]
	v_mfma_f32_16x16x32_f16 v[40:43], v[192:195], v[160:163], v[40:43]
	v_mfma_f32_16x16x32_f16 v[20:23], v[184:187], v[168:171], v[20:23]
	v_mfma_f32_16x16x32_f16 v[24:27], v[192:195], v[168:171], v[24:27]
	v_mfma_f32_16x16x32_f16 v[8:11], v[184:187], v[176:179], v[8:11]
	v_mfma_f32_16x16x32_f16 v[4:7], v[192:195], v[176:179], v[4:7]
	s_setprio 0
	v_add_u32_e32 v1, s99, v238
	s_barrier
	ds_read_b128 v[132:135], v1
	ds_read_b128 v[136:139], v1 offset:1024
	ds_read_b128 v[140:143], v1 offset:2048
	ds_read_b128 v[144:147], v1 offset:3072
	s_add_u32 s10, s10, s28
	s_addc_u32 s11, s11, s29
	s_mov_b32 m0, s79
	v_lshl_add_u64 v[180:181], s[10:11], 0, v[200:201]
	ds_read_b128 v[148:151], v240 offset:32768
	ds_read_b128 v[152:155], v240 offset:33792
	ds_read_b128 v[156:159], v240 offset:34816
	ds_read_b128 v[160:163], v240 offset:35840
	ds_read_b128 v[164:167], v240 offset:36864
	ds_read_b128 v[168:171], v240 offset:37888
	ds_read_b128 v[172:175], v240 offset:38912
	ds_read_b128 v[176:179], v240 offset:39936
	global_load_lds_dwordx4 v[180:181], off
	v_lshl_add_u64 v[180:181], s[10:11], 0, v[202:203]
	s_mov_b32 m0, s60
	s_nop 0
	global_load_lds_dwordx4 v[180:181], off
	s_waitcnt lgkmcnt(8)
	s_waitcnt vmcnt(10)
	s_barrier
	s_waitcnt lgkmcnt(0)
	s_setprio 1
	s_waitcnt lgkmcnt(0)
	v_mfma_f32_16x16x32_f16 v[124:127], v[132:135], v[148:151], v[124:127]
	v_mfma_f32_16x16x32_f16 v[128:131], v[140:143], v[148:151], v[128:131]
	v_mfma_f32_16x16x32_f16 v[108:111], v[132:135], v[156:159], v[108:111]
	v_mfma_f32_16x16x32_f16 v[112:115], v[140:143], v[156:159], v[112:115]
	v_mfma_f32_16x16x32_f16 v[92:95], v[132:135], v[164:167], v[92:95]
	v_mfma_f32_16x16x32_f16 v[96:99], v[140:143], v[164:167], v[96:99]
	v_mfma_f32_16x16x32_f16 v[76:79], v[132:135], v[172:175], v[76:79]
	v_mfma_f32_16x16x32_f16 v[80:83], v[140:143], v[172:175], v[80:83]
	v_mfma_f32_16x16x32_f16 v[124:127], v[136:139], v[152:155], v[124:127]
	v_mfma_f32_16x16x32_f16 v[128:131], v[144:147], v[152:155], v[128:131]
	v_mfma_f32_16x16x32_f16 v[108:111], v[136:139], v[160:163], v[108:111]
	v_mfma_f32_16x16x32_f16 v[112:115], v[144:147], v[160:163], v[112:115]
	v_mfma_f32_16x16x32_f16 v[92:95], v[136:139], v[168:171], v[92:95]
	v_mfma_f32_16x16x32_f16 v[96:99], v[144:147], v[168:171], v[96:99]
	v_mfma_f32_16x16x32_f16 v[76:79], v[136:139], v[176:179], v[76:79]
	v_mfma_f32_16x16x32_f16 v[80:83], v[144:147], v[176:179], v[80:83]
	s_setprio 0
	s_barrier
	s_add_i32 s10, 0, 0x1c000
	s_add_i32 s11, s99, s72
	v_add_u32_e32 v1, s10, v238
	v_lshl_add_u64 v[210:211], v[210:211], 0, s[86:87]
	s_mov_b32 m0, s11
	ds_read_b128 v[180:183], v1
	ds_read_b128 v[184:187], v1 offset:1024
	ds_read_b128 v[188:191], v1 offset:2048
	ds_read_b128 v[192:195], v1 offset:3072
	global_load_lds_dwordx4 v[210:211], off
	v_lshl_add_u64 v[210:211], v[212:213], 0, s[86:87]
	s_add_i32 m0, s11, 0x2000
	s_nop 0
	global_load_lds_dwordx4 v[210:211], off
	s_waitcnt vmcnt(10)
	s_barrier
	s_waitcnt lgkmcnt(0)
	s_setprio 1
	s_waitcnt lgkmcnt(0)
	v_mfma_f32_16x16x32_f16 v[116:119], v[180:183], v[148:151], v[116:119]
	v_mfma_f32_16x16x32_f16 v[120:123], v[188:191], v[148:151], v[120:123]
	v_mfma_f32_16x16x32_f16 v[100:103], v[180:183], v[156:159], v[100:103]
	v_mfma_f32_16x16x32_f16 v[104:107], v[188:191], v[156:159], v[104:107]
	v_mfma_f32_16x16x32_f16 v[84:87], v[180:183], v[164:167], v[84:87]
	v_mfma_f32_16x16x32_f16 v[88:91], v[188:191], v[164:167], v[88:91]
	v_mfma_f32_16x16x32_f16 v[68:71], v[180:183], v[172:175], v[68:71]
	v_mfma_f32_16x16x32_f16 v[72:75], v[188:191], v[172:175], v[72:75]
	v_mfma_f32_16x16x32_f16 v[116:119], v[184:187], v[152:155], v[116:119]
	v_mfma_f32_16x16x32_f16 v[120:123], v[192:195], v[152:155], v[120:123]
	v_mfma_f32_16x16x32_f16 v[100:103], v[184:187], v[160:163], v[100:103]
	v_mfma_f32_16x16x32_f16 v[104:107], v[192:195], v[160:163], v[104:107]
	v_mfma_f32_16x16x32_f16 v[84:87], v[184:187], v[168:171], v[84:87]
	v_mfma_f32_16x16x32_f16 v[88:91], v[192:195], v[168:171], v[88:91]
	v_mfma_f32_16x16x32_f16 v[68:71], v[184:187], v[176:179], v[68:71]
	v_mfma_f32_16x16x32_f16 v[72:75], v[192:195], v[176:179], v[72:75]
	s_setprio 0
	s_mov_b32 m0, s77
	v_lshl_add_u64 v[210:211], v[214:215], 0, s[86:87]
	s_barrier
	ds_read_b128 v[148:151], v240 offset:49152
	ds_read_b128 v[152:155], v240 offset:50176
	ds_read_b128 v[156:159], v240 offset:51200
	ds_read_b128 v[160:163], v240 offset:52224
	ds_read_b128 v[164:167], v240 offset:53248
	ds_read_b128 v[168:171], v240 offset:54272
	ds_read_b128 v[172:175], v240 offset:55296
	ds_read_b128 v[176:179], v240 offset:56320
	global_load_lds_dwordx4 v[210:211], off
	v_lshl_add_u64 v[210:211], v[216:217], 0, s[86:87]
	s_mov_b32 m0, s64
	s_nop 0
	global_load_lds_dwordx4 v[210:211], off
	s_barrier
	s_waitcnt lgkmcnt(0)
	s_setprio 1
	s_waitcnt lgkmcnt(0)
	v_mfma_f32_16x16x32_f16 v[60:63], v[132:135], v[148:151], v[60:63]
	v_mfma_f32_16x16x32_f16 v[64:67], v[140:143], v[148:151], v[64:67]
	v_mfma_f32_16x16x32_f16 v[44:47], v[132:135], v[156:159], v[44:47]
	v_mfma_f32_16x16x32_f16 v[48:51], v[140:143], v[156:159], v[48:51]
	v_mfma_f32_16x16x32_f16 v[28:31], v[132:135], v[164:167], v[28:31]
	v_mfma_f32_16x16x32_f16 v[32:35], v[140:143], v[164:167], v[32:35]
	v_mfma_f32_16x16x32_f16 v[12:15], v[132:135], v[172:175], v[12:15]
	v_mfma_f32_16x16x32_f16 v[16:19], v[140:143], v[172:175], v[16:19]
	v_mfma_f32_16x16x32_f16 v[60:63], v[136:139], v[152:155], v[60:63]
	v_mfma_f32_16x16x32_f16 v[64:67], v[144:147], v[152:155], v[64:67]
	v_mfma_f32_16x16x32_f16 v[44:47], v[136:139], v[160:163], v[44:47]
	v_mfma_f32_16x16x32_f16 v[48:51], v[144:147], v[160:163], v[48:51]
	v_mfma_f32_16x16x32_f16 v[28:31], v[136:139], v[168:171], v[28:31]
	v_mfma_f32_16x16x32_f16 v[32:35], v[144:147], v[168:171], v[32:35]
	v_mfma_f32_16x16x32_f16 v[12:15], v[136:139], v[176:179], v[12:15]
	v_mfma_f32_16x16x32_f16 v[16:19], v[144:147], v[176:179], v[16:19]
	s_setprio 0
	s_barrier
	s_add_i32 s10, s10, s72
	v_lshl_add_u64 v[132:133], v[218:219], 0, s[86:87]
	s_mov_b32 m0, s10
	s_nop 0
	global_load_lds_dwordx4 v[132:133], off
	v_lshl_add_u64 v[132:133], v[220:221], 0, s[86:87]
	s_add_i32 m0, s10, 0x2000
	s_nop 0
	global_load_lds_dwordx4 v[132:133], off
	s_waitcnt vmcnt(10)
	s_barrier
	s_setprio 1
	v_mfma_f32_16x16x32_f16 v[52:55], v[180:183], v[148:151], v[52:55]
	v_mfma_f32_16x16x32_f16 v[56:59], v[188:191], v[148:151], v[56:59]
	v_mfma_f32_16x16x32_f16 v[36:39], v[180:183], v[156:159], v[36:39]
	v_mfma_f32_16x16x32_f16 v[40:43], v[188:191], v[156:159], v[40:43]
	v_mfma_f32_16x16x32_f16 v[20:23], v[180:183], v[164:167], v[20:23]
	v_mfma_f32_16x16x32_f16 v[24:27], v[188:191], v[164:167], v[24:27]
	v_mfma_f32_16x16x32_f16 v[8:11], v[180:183], v[172:175], v[8:11]
	v_mfma_f32_16x16x32_f16 v[4:7], v[188:191], v[172:175], v[4:7]
	v_mfma_f32_16x16x32_f16 v[52:55], v[184:187], v[152:155], v[52:55]
	v_mfma_f32_16x16x32_f16 v[56:59], v[192:195], v[152:155], v[56:59]
	v_mfma_f32_16x16x32_f16 v[36:39], v[184:187], v[160:163], v[36:39]
	v_mfma_f32_16x16x32_f16 v[40:43], v[192:195], v[160:163], v[40:43]
	v_mfma_f32_16x16x32_f16 v[20:23], v[184:187], v[168:171], v[20:23]
	v_mfma_f32_16x16x32_f16 v[24:27], v[192:195], v[168:171], v[24:27]
	v_mfma_f32_16x16x32_f16 v[8:11], v[184:187], v[176:179], v[8:11]
	v_mfma_f32_16x16x32_f16 v[4:7], v[192:195], v[176:179], v[4:7]
	s_setprio 0
	s_add_u32 s4, s4, 0x100
	s_addc_u32 s5, s5, 0
	s_add_u32 s1, s1, 0x100
	s_addc_u32 vcc_lo, vcc_lo, 0
	s_cmp_ge_i32 vcc_hi, s67
	s_mov_b32 s10, vcc_hi
	s_barrier
	s_cbranch_scc1 .LBB0_377
	s_branch .LBB0_376
.Lk_goB:
	s_add_i32 vcc_hi, s10, 2
	s_add_u32 s56, s4, 0x80
	s_addc_u32 s11, s5, 0
	s_add_i32 s98, 0, 0x10000
	v_add_u32_e32 v1, s98, v238
	ds_read_b128 v[132:135], v1
	ds_read_b128 v[136:139], v1 offset:1024
	ds_read_b128 v[140:143], v1 offset:2048
	ds_read_b128 v[144:147], v1 offset:3072
	s_cmp_eq_u32 s75, s10
	s_cselect_b32 s10, s50, s56
	s_cselect_b32 s11, s51, s11
	s_cselect_b32 s57, s97, vcc_lo
	s_cselect_b32 s56, s96, s1
	v_lshl_add_u64 v[180:181], s[4:5], 0, v[206:207]
	s_add_i32 m0, s73, 0xc000
	ds_read_b128 v[148:151], v240
	ds_read_b128 v[152:155], v240 offset:1024
	ds_read_b128 v[156:159], v240 offset:2048
	ds_read_b128 v[160:163], v240 offset:3072
	ds_read_b128 v[164:167], v240 offset:4096
	ds_read_b128 v[168:171], v240 offset:5120
	ds_read_b128 v[172:175], v240 offset:6144
	ds_read_b128 v[176:179], v240 offset:7168
	global_load_lds_dwordx4 v[180:181], off
	v_lshl_add_u64 v[180:181], s[4:5], 0, v[208:209]
	s_add_i32 m0, s73, 0xe000
	s_nop 0
	global_load_lds_dwordx4 v[180:181], off
	s_waitcnt lgkmcnt(8)
	s_waitcnt vmcnt(18)
	s_barrier
	s_waitcnt lgkmcnt(0)
	s_setprio 1
	s_waitcnt lgkmcnt(0)
	v_mfma_f32_16x16x32_f16 v[124:127], v[132:135], v[148:151], 0
	v_mfma_f32_16x16x32_f16 v[128:131], v[140:143], v[148:151], 0
	v_mfma_f32_16x16x32_f16 v[108:111], v[132:135], v[156:159], 0
	v_mfma_f32_16x16x32_f16 v[112:115], v[140:143], v[156:159], 0
	v_mfma_f32_16x16x32_f16 v[92:95], v[132:135], v[164:167], 0
	v_mfma_f32_16x16x32_f16 v[96:99], v[140:143], v[164:167], 0
	v_mfma_f32_16x16x32_f16 v[76:79], v[132:135], v[172:175], 0
	v_mfma_f32_16x16x32_f16 v[80:83], v[140:143], v[172:175], 0
	v_mfma_f32_16x16x32_f16 v[124:127], v[136:139], v[152:155], v[124:127]
	v_mfma_f32_16x16x32_f16 v[128:131], v[144:147], v[152:155], v[128:131]
	v_mfma_f32_16x16x32_f16 v[108:111], v[136:139], v[160:163], v[108:111]
	v_mfma_f32_16x16x32_f16 v[112:115], v[144:147], v[160:163], v[112:115]
	v_mfma_f32_16x16x32_f16 v[92:95], v[136:139], v[168:171], v[92:95]
	v_mfma_f32_16x16x32_f16 v[96:99], v[144:147], v[168:171], v[96:99]
	v_mfma_f32_16x16x32_f16 v[76:79], v[136:139], v[176:179], v[76:79]
	v_mfma_f32_16x16x32_f16 v[80:83], v[144:147], v[176:179], v[80:83]
	s_setprio 0
	s_barrier
	s_add_i32 s98, s98, s72
	v_add_u32_e32 v1, s58, v238
	v_lshl_add_u64 v[210:211], s[56:57], 0, v[200:201]
	s_mov_b32 m0, s98
	ds_read_b128 v[180:183], v1
	ds_read_b128 v[184:187], v1 offset:1024
	ds_read_b128 v[188:191], v1 offset:2048
	ds_read_b128 v[192:195], v1 offset:3072
	global_load_lds_dwordx4 v[210:211], off
	v_lshl_add_u64 v[212:213], s[56:57], 0, v[202:203]
	s_add_i32 m0, s98, 0x2000
	s_nop 0
	global_load_lds_dwordx4 v[212:213], off
	s_waitcnt vmcnt(18)
	s_barrier
	s_waitcnt lgkmcnt(0)
	s_setprio 1
	s_waitcnt lgkmcnt(0)
	v_mfma_f32_16x16x32_f16 v[116:119], v[180:183], v[148:151], 0
	v_mfma_f32_16x16x32_f16 v[120:123], v[188:191], v[148:151], 0
	v_mfma_f32_16x16x32_f16 v[100:103], v[180:183], v[156:159], 0
	v_mfma_f32_16x16x32_f16 v[104:107], v[188:191], v[156:159], 0
	v_mfma_f32_16x16x32_f16 v[84:87], v[180:183], v[164:167], 0
	v_mfma_f32_16x16x32_f16 v[88:91], v[188:191], v[164:167], 0
	v_mfma_f32_16x16x32_f16 v[68:71], v[180:183], v[172:175], 0
	v_mfma_f32_16x16x32_f16 v[72:75], v[188:191], v[172:175], 0
	v_mfma_f32_16x16x32_f16 v[116:119], v[184:187], v[152:155], v[116:119]
	v_mfma_f32_16x16x32_f16 v[120:123], v[192:195], v[152:155], v[120:123]
	v_mfma_f32_16x16x32_f16 v[100:103], v[184:187], v[160:163], v[100:103]
	v_mfma_f32_16x16x32_f16 v[104:107], v[192:195], v[160:163], v[104:107]
	v_mfma_f32_16x16x32_f16 v[84:87], v[184:187], v[168:171], v[84:87]
	v_mfma_f32_16x16x32_f16 v[88:91], v[192:195], v[168:171], v[88:91]
	v_mfma_f32_16x16x32_f16 v[68:71], v[184:187], v[176:179], v[68:71]
	v_mfma_f32_16x16x32_f16 v[72:75], v[192:195], v[176:179], v[72:75]
	s_setprio 0
	s_mov_b32 m0, s73
	v_lshl_add_u64 v[214:215], s[10:11], 0, v[200:201]
	s_barrier
	ds_read_b128 v[148:151], v240 offset:16384
	ds_read_b128 v[152:155], v240 offset:17408
	ds_read_b128 v[156:159], v240 offset:18432
	ds_read_b128 v[160:163], v240 offset:19456
	ds_read_b128 v[164:167], v240 offset:20480
	ds_read_b128 v[168:171], v240 offset:21504
	ds_read_b128 v[172:175], v240 offset:22528
	ds_read_b128 v[176:179], v240 offset:23552
	global_load_lds_dwordx4 v[214:215], off
	v_lshl_add_u64 v[216:217], s[10:11], 0, v[202:203]
	s_mov_b32 m0, s78
	s_nop 0
	global_load_lds_dwordx4 v[216:217], off
	s_barrier
	s_waitcnt lgkmcnt(0)
	s_setprio 1
	s_waitcnt lgkmcnt(0)
	v_mfma_f32_16x16x32_f16 v[60:63], v[132:135], v[148:151], 0
	v_mfma_f32_16x16x32_f16 v[64:67], v[140:143], v[148:151], 0
	v_mfma_f32_16x16x32_f16 v[44:47], v[132:135], v[156:159], 0
	v_mfma_f32_16x16x32_f16 v[48:51], v[140:143], v[156:159], 0
	v_mfma_f32_16x16x32_f16 v[28:31], v[132:135], v[164:167], 0
	v_mfma_f32_16x16x32_f16 v[32:35], v[140:143], v[164:167], 0
	v_mfma_f32_16x16x32_f16 v[12:15], v[132:135], v[172:175], 0
	v_mfma_f32_16x16x32_f16 v[16:19], v[140:143], v[172:175], 0
	v_mfma_f32_16x16x32_f16 v[60:63], v[136:139], v[152:155], v[60:63]
	v_mfma_f32_16x16x32_f16 v[64:67], v[144:147], v[152:155], v[64:67]
	v_mfma_f32_16x16x32_f16 v[44:47], v[136:139], v[160:163], v[44:47]
	v_mfma_f32_16x16x32_f16 v[48:51], v[144:147], v[160:163], v[48:51]
	v_mfma_f32_16x16x32_f16 v[28:31], v[136:139], v[168:171], v[28:31]
	v_mfma_f32_16x16x32_f16 v[32:35], v[144:147], v[168:171], v[32:35]
	v_mfma_f32_16x16x32_f16 v[12:15], v[136:139], v[176:179], v[12:15]
	v_mfma_f32_16x16x32_f16 v[16:19], v[144:147], v[176:179], v[16:19]
	s_setprio 0
	s_barrier
	s_add_u32 s56, s56, s28
	s_addc_u32 s57, s57, s29
	s_add_i32 s98, s58, s72
	v_lshl_add_u64 v[218:219], s[56:57], 0, v[200:201]
	s_mov_b32 m0, s98
	v_lshl_add_u64 v[220:221], s[56:57], 0, v[202:203]
	global_load_lds_dwordx4 v[218:219], off
	s_add_i32 m0, s98, 0x2000
	s_nop 0
	global_load_lds_dwordx4 v[220:221], off
	s_waitcnt vmcnt(18)
	s_barrier
	s_setprio 1
	v_mfma_f32_16x16x32_f16 v[52:55], v[180:183], v[148:151], 0
	v_mfma_f32_16x16x32_f16 v[56:59], v[188:191], v[148:151], 0
	v_mfma_f32_16x16x32_f16 v[36:39], v[180:183], v[156:159], 0
	v_mfma_f32_16x16x32_f16 v[40:43], v[188:191], v[156:159], 0
	v_mfma_f32_16x16x32_f16 v[20:23], v[180:183], v[164:167], 0
	v_mfma_f32_16x16x32_f16 v[24:27], v[188:191], v[164:167], 0
	v_mfma_f32_16x16x32_f16 v[8:11], v[180:183], v[172:175], 0
	v_mfma_f32_16x16x32_f16 v[4:7], v[188:191], v[172:175], 0
	v_mfma_f32_16x16x32_f16 v[52:55], v[184:187], v[152:155], v[52:55]
	v_mfma_f32_16x16x32_f16 v[56:59], v[192:195], v[152:155], v[56:59]
	v_mfma_f32_16x16x32_f16 v[36:39], v[184:187], v[160:163], v[36:39]
	v_mfma_f32_16x16x32_f16 v[40:43], v[192:195], v[160:163], v[40:43]
	v_mfma_f32_16x16x32_f16 v[20:23], v[184:187], v[168:171], v[20:23]
	v_mfma_f32_16x16x32_f16 v[24:27], v[192:195], v[168:171], v[24:27]
	v_mfma_f32_16x16x32_f16 v[8:11], v[184:187], v[176:179], v[8:11]
	v_mfma_f32_16x16x32_f16 v[4:7], v[192:195], v[176:179], v[4:7]
	s_setprio 0
	v_add_u32_e32 v1, s99, v238
	s_barrier
	ds_read_b128 v[132:135], v1
	ds_read_b128 v[136:139], v1 offset:1024
	ds_read_b128 v[140:143], v1 offset:2048
	ds_read_b128 v[144:147], v1 offset:3072
	s_add_u32 s10, s10, s28
	s_addc_u32 s11, s11, s29
	s_mov_b32 m0, s79
	v_lshl_add_u64 v[180:181], s[10:11], 0, v[200:201]
	ds_read_b128 v[148:151], v240 offset:32768
	ds_read_b128 v[152:155], v240 offset:33792
	ds_read_b128 v[156:159], v240 offset:34816
	ds_read_b128 v[160:163], v240 offset:35840
	ds_read_b128 v[164:167], v240 offset:36864
	ds_read_b128 v[168:171], v240 offset:37888
	ds_read_b128 v[172:175], v240 offset:38912
	ds_read_b128 v[176:179], v240 offset:39936
	global_load_lds_dwordx4 v[180:181], off
	v_lshl_add_u64 v[180:181], s[10:11], 0, v[202:203]
	s_mov_b32 m0, s60
	s_nop 0
	global_load_lds_dwordx4 v[180:181], off
	s_waitcnt lgkmcnt(8)
	s_waitcnt vmcnt(18)
	s_barrier
	s_waitcnt lgkmcnt(0)
	s_setprio 1
	s_waitcnt lgkmcnt(0)
	v_mfma_f32_16x16x32_f16 v[124:127], v[132:135], v[148:151], v[124:127]
	v_mfma_f32_16x16x32_f16 v[128:131], v[140:143], v[148:151], v[128:131]
	v_mfma_f32_16x16x32_f16 v[108:111], v[132:135], v[156:159], v[108:111]
	v_mfma_f32_16x16x32_f16 v[112:115], v[140:143], v[156:159], v[112:115]
	v_mfma_f32_16x16x32_f16 v[92:95], v[132:135], v[164:167], v[92:95]
	v_mfma_f32_16x16x32_f16 v[96:99], v[140:143], v[164:167], v[96:99]
	v_mfma_f32_16x16x32_f16 v[76:79], v[132:135], v[172:175], v[76:79]
	v_mfma_f32_16x16x32_f16 v[80:83], v[140:143], v[172:175], v[80:83]
	v_mfma_f32_16x16x32_f16 v[124:127], v[136:139], v[152:155], v[124:127]
	v_mfma_f32_16x16x32_f16 v[128:131], v[144:147], v[152:155], v[128:131]
	v_mfma_f32_16x16x32_f16 v[108:111], v[136:139], v[160:163], v[108:111]
	v_mfma_f32_16x16x32_f16 v[112:115], v[144:147], v[160:163], v[112:115]
	v_mfma_f32_16x16x32_f16 v[92:95], v[136:139], v[168:171], v[92:95]
	v_mfma_f32_16x16x32_f16 v[96:99], v[144:147], v[168:171], v[96:99]
	v_mfma_f32_16x16x32_f16 v[76:79], v[136:139], v[176:179], v[76:79]
	v_mfma_f32_16x16x32_f16 v[80:83], v[144:147], v[176:179], v[80:83]
	s_setprio 0
	s_barrier
	s_add_i32 s10, 0, 0x1c000
	s_add_i32 s11, s99, s72
	v_add_u32_e32 v1, s10, v238
	v_lshl_add_u64 v[210:211], v[210:211], 0, s[86:87]
	s_mov_b32 m0, s11
	ds_read_b128 v[180:183], v1
	ds_read_b128 v[184:187], v1 offset:1024
	ds_read_b128 v[188:191], v1 offset:2048
	ds_read_b128 v[192:195], v1 offset:3072
	global_load_lds_dwordx4 v[210:211], off
	v_lshl_add_u64 v[210:211], v[212:213], 0, s[86:87]
	s_add_i32 m0, s11, 0x2000
	s_nop 0
	global_load_lds_dwordx4 v[210:211], off
	s_waitcnt vmcnt(18)
	s_barrier
	s_waitcnt lgkmcnt(0)
	s_setprio 1
	s_waitcnt lgkmcnt(0)
	v_mfma_f32_16x16x32_f16 v[116:119], v[180:183], v[148:151], v[116:119]
	v_mfma_f32_16x16x32_f16 v[120:123], v[188:191], v[148:151], v[120:123]
	v_mfma_f32_16x16x32_f16 v[100:103], v[180:183], v[156:159], v[100:103]
	v_mfma_f32_16x16x32_f16 v[104:107], v[188:191], v[156:159], v[104:107]
	v_mfma_f32_16x16x32_f16 v[84:87], v[180:183], v[164:167], v[84:87]
	v_mfma_f32_16x16x32_f16 v[88:91], v[188:191], v[164:167], v[88:91]
	v_mfma_f32_16x16x32_f16 v[68:71], v[180:183], v[172:175], v[68:71]
	v_mfma_f32_16x16x32_f16 v[72:75], v[188:191], v[172:175], v[72:75]
	v_mfma_f32_16x16x32_f16 v[116:119], v[184:187], v[152:155], v[116:119]
	v_mfma_f32_16x16x32_f16 v[120:123], v[192:195], v[152:155], v[120:123]
	v_mfma_f32_16x16x32_f16 v[100:103], v[184:187], v[160:163], v[100:103]
	v_mfma_f32_16x16x32_f16 v[104:107], v[192:195], v[160:163], v[104:107]
	v_mfma_f32_16x16x32_f16 v[84:87], v[184:187], v[168:171], v[84:87]
	v_mfma_f32_16x16x32_f16 v[88:91], v[192:195], v[168:171], v[88:91]
	v_mfma_f32_16x16x32_f16 v[68:71], v[184:187], v[176:179], v[68:71]
	v_mfma_f32_16x16x32_f16 v[72:75], v[192:195], v[176:179], v[72:75]
	s_setprio 0
	s_mov_b32 m0, s77
	v_lshl_add_u64 v[210:211], v[214:215], 0, s[86:87]
	s_barrier
	ds_read_b128 v[148:151], v240 offset:49152
	ds_read_b128 v[152:155], v240 offset:50176
	ds_read_b128 v[156:159], v240 offset:51200
	ds_read_b128 v[160:163], v240 offset:52224
	ds_read_b128 v[164:167], v240 offset:53248
	ds_read_b128 v[168:171], v240 offset:54272
	ds_read_b128 v[172:175], v240 offset:55296
	ds_read_b128 v[176:179], v240 offset:56320
	global_load_lds_dwordx4 v[210:211], off
	v_lshl_add_u64 v[210:211], v[216:217], 0, s[86:87]
	s_mov_b32 m0, s64
	s_nop 0
	global_load_lds_dwordx4 v[210:211], off
	s_barrier
	s_waitcnt lgkmcnt(0)
	s_setprio 1
	s_waitcnt lgkmcnt(0)
	v_mfma_f32_16x16x32_f16 v[60:63], v[132:135], v[148:151], v[60:63]
	v_mfma_f32_16x16x32_f16 v[64:67], v[140:143], v[148:151], v[64:67]
	v_mfma_f32_16x16x32_f16 v[44:47], v[132:135], v[156:159], v[44:47]
	v_mfma_f32_16x16x32_f16 v[48:51], v[140:143], v[156:159], v[48:51]
	v_mfma_f32_16x16x32_f16 v[28:31], v[132:135], v[164:167], v[28:31]
	v_mfma_f32_16x16x32_f16 v[32:35], v[140:143], v[164:167], v[32:35]
	v_mfma_f32_16x16x32_f16 v[12:15], v[132:135], v[172:175], v[12:15]
	v_mfma_f32_16x16x32_f16 v[16:19], v[140:143], v[172:175], v[16:19]
	v_mfma_f32_16x16x32_f16 v[60:63], v[136:139], v[152:155], v[60:63]
	v_mfma_f32_16x16x32_f16 v[64:67], v[144:147], v[152:155], v[64:67]
	v_mfma_f32_16x16x32_f16 v[44:47], v[136:139], v[160:163], v[44:47]
	v_mfma_f32_16x16x32_f16 v[48:51], v[144:147], v[160:163], v[48:51]
	v_mfma_f32_16x16x32_f16 v[28:31], v[136:139], v[168:171], v[28:31]
	v_mfma_f32_16x16x32_f16 v[32:35], v[144:147], v[168:171], v[32:35]
	v_mfma_f32_16x16x32_f16 v[12:15], v[136:139], v[176:179], v[12:15]
	v_mfma_f32_16x16x32_f16 v[16:19], v[144:147], v[176:179], v[16:19]
	s_setprio 0
	s_barrier
	s_add_i32 s10, s10, s72
	v_lshl_add_u64 v[132:133], v[218:219], 0, s[86:87]
	s_mov_b32 m0, s10
	s_nop 0
	global_load_lds_dwordx4 v[132:133], off
	v_lshl_add_u64 v[132:133], v[220:221], 0, s[86:87]
	s_add_i32 m0, s10, 0x2000
	s_nop 0
	global_load_lds_dwordx4 v[132:133], off
	s_waitcnt vmcnt(18)
	s_barrier
	s_setprio 1
	v_mfma_f32_16x16x32_f16 v[52:55], v[180:183], v[148:151], v[52:55]
	v_mfma_f32_16x16x32_f16 v[56:59], v[188:191], v[148:151], v[56:59]
	v_mfma_f32_16x16x32_f16 v[36:39], v[180:183], v[156:159], v[36:39]
	v_mfma_f32_16x16x32_f16 v[40:43], v[188:191], v[156:159], v[40:43]
	v_mfma_f32_16x16x32_f16 v[20:23], v[180:183], v[164:167], v[20:23]
	v_mfma_f32_16x16x32_f16 v[24:27], v[188:191], v[164:167], v[24:27]
	v_mfma_f32_16x16x32_f16 v[8:11], v[180:183], v[172:175], v[8:11]
	v_mfma_f32_16x16x32_f16 v[4:7], v[188:191], v[172:175], v[4:7]
	v_mfma_f32_16x16x32_f16 v[52:55], v[184:187], v[152:155], v[52:55]
	v_mfma_f32_16x16x32_f16 v[56:59], v[192:195], v[152:155], v[56:59]
	v_mfma_f32_16x16x32_f16 v[36:39], v[184:187], v[160:163], v[36:39]
	v_mfma_f32_16x16x32_f16 v[40:43], v[192:195], v[160:163], v[40:43]
	v_mfma_f32_16x16x32_f16 v[20:23], v[184:187], v[168:171], v[20:23]
	v_mfma_f32_16x16x32_f16 v[24:27], v[192:195], v[168:171], v[24:27]
	v_mfma_f32_16x16x32_f16 v[8:11], v[184:187], v[176:179], v[8:11]
	v_mfma_f32_16x16x32_f16 v[4:7], v[192:195], v[176:179], v[4:7]
	s_setprio 0
	s_add_u32 s4, s4, 0x100
	s_addc_u32 s5, s5, 0
	s_add_u32 s1, s1, 0x100
	s_addc_u32 vcc_lo, vcc_lo, 0
	s_cmp_ge_i32 vcc_hi, s67
	s_mov_b32 s10, vcc_hi
	s_barrier
	s_cbranch_scc1 .LBB0_377
